# kv item and gla_out item start: first load group's wait+LDS write block moved behind the issue of the second load group (two round trips overlap)
# speedup vs baseline: 1.0010x; 1.0010x over previous
.LBB0_501:
	s_ashr_i32 s28, s27, 2
	s_lshl_b32 s0, s28, 6
	s_ashr_i32 s1, s0, 31
	s_lshl_b64 s[20:21], s[0:1], 7
	v_lshl_add_u64 v[0:1], v[88:89], 0, s[20:21]
	global_load_dwordx4 v[240:243], v[0:1], off
	s_and_b32 s9, s27, 3
	s_mul_i32 s1, s28, 0x60000
	s_mul_hi_i32 s8, s0, 0x1800
	s_add_u32 s0, s90, s1
	s_addc_u32 s1, s91, s8
	s_lshl_b32 s8, s9, 8
	s_lshl_b32 s20, s9, 9
	s_add_u32 s20, s0, s20
	s_addc_u32 s21, s1, 0
	v_mov_b32_e32 v189, v91
	s_lshl_b32 s29, s9, 7
	s_movk_i32 s9, 0x1000
	s_add_u32 s0, s0, s8
	s_addc_u32 s1, s1, 0
	v_mov_b32_e32 v26, v204
	v_mov_b32_e32 v27, v91
	v_lshl_add_u64 v[0:1], s[20:21], 0, v[188:189]
	v_lshl_add_u64 v[2:3], v[0:1], 0, v[92:93]
	global_load_ushort v208, v[2:3], off offset:2048
	v_lshl_add_u64 v[2:3], v[0:1], 0, v[94:95]
	global_load_ushort v209, v[2:3], off offset:2048
	v_lshl_add_u64 v[2:3], v[0:1], 0, v[96:97]
	global_load_ushort v210, v[2:3], off offset:2048
	v_lshl_add_u64 v[2:3], v[0:1], 0, v[98:99]
	global_load_ushort v211, v[2:3], off offset:2048
	v_lshl_add_u64 v[2:3], v[0:1], 0, v[100:101]
	global_load_ushort v212, v[2:3], off offset:2048
	v_lshl_add_u64 v[2:3], v[0:1], 0, v[102:103]
	global_load_ushort v213, v[2:3], off offset:2048
	v_lshl_add_u64 v[2:3], v[0:1], 0, v[104:105]
	global_load_ushort v214, v[2:3], off offset:2048
	v_lshl_add_u64 v[2:3], v[0:1], 0, v[106:107]
	global_load_ushort v215, v[2:3], off offset:2048
	v_lshl_add_u64 v[2:3], v[0:1], 0, v[108:109]
	global_load_ushort v216, v[2:3], off offset:2048
	v_lshl_add_u64 v[2:3], v[0:1], 0, v[110:111]
	global_load_ushort v217, v[2:3], off offset:2048
	v_lshl_add_u64 v[2:3], v[0:1], 0, v[112:113]
	global_load_ushort v218, v[2:3], off offset:2048
	v_lshl_add_u64 v[2:3], v[0:1], 0, v[114:115]
	global_load_ushort v219, v[2:3], off offset:2048
	v_lshl_add_u64 v[2:3], v[0:1], 0, v[116:117]
	global_load_ushort v220, v[2:3], off offset:2048
	v_lshl_add_u64 v[2:3], v[0:1], 0, v[118:119]
	global_load_ushort v221, v[2:3], off offset:2048
	v_lshl_add_u64 v[2:3], v[0:1], 0, v[120:121]
	global_load_ushort v222, v[2:3], off offset:2048
	v_lshl_add_u64 v[2:3], v[0:1], 0, v[122:123]
	global_load_ushort v223, v[2:3], off offset:2048
	v_lshl_add_u64 v[2:3], v[0:1], 0, v[124:125]
	global_load_ushort v224, v[2:3], off offset:2048
	v_lshl_add_u64 v[2:3], v[0:1], 0, v[126:127]
	global_load_ushort v225, v[2:3], off offset:2048
	v_lshl_add_u64 v[2:3], v[0:1], 0, v[128:129]
	global_load_ushort v226, v[2:3], off offset:2048
	v_lshl_add_u64 v[2:3], v[0:1], 0, v[130:131]
	global_load_ushort v227, v[2:3], off offset:2048
	v_lshl_add_u64 v[2:3], v[0:1], 0, v[132:133]
	global_load_ushort v228, v[2:3], off offset:2048
	v_lshl_add_u64 v[2:3], v[0:1], 0, v[134:135]
	global_load_ushort v229, v[2:3], off offset:2048
	v_lshl_add_u64 v[2:3], v[0:1], 0, v[136:137]
	global_load_ushort v230, v[2:3], off offset:2048
	v_lshl_add_u64 v[2:3], v[0:1], 0, v[138:139]
	global_load_ushort v231, v[2:3], off offset:2048
	v_lshl_add_u64 v[2:3], v[0:1], 0, v[140:141]
	global_load_ushort v232, v[2:3], off offset:2048
	v_lshl_add_u64 v[2:3], v[0:1], 0, v[142:143]
	global_load_ushort v233, v[2:3], off offset:2048
	v_lshl_add_u64 v[2:3], v[0:1], 0, v[144:145]
	global_load_ushort v234, v[2:3], off offset:2048
	v_lshl_add_u64 v[2:3], v[0:1], 0, v[146:147]
	global_load_ushort v235, v[2:3], off offset:2048
	v_lshl_add_u64 v[2:3], v[0:1], 0, v[148:149]
	global_load_ushort v236, v[2:3], off offset:2048
	v_lshl_add_u64 v[2:3], v[0:1], 0, v[150:151]
	global_load_ushort v237, v[2:3], off offset:2048
	v_lshl_add_u64 v[2:3], v[0:1], 0, v[152:153]
	v_lshl_add_u64 v[0:1], v[0:1], 0, v[154:155]
	global_load_ushort v238, v[2:3], off offset:2048
	global_load_ushort v239, v[0:1], off offset:2048
	v_or_b32_e32 v0, s29, v156
	v_lshlrev_b32_e32 v90, 2, v0
	v_lshl_add_u64 v[16:17], v[158:159], 0, v[90:91]
	v_add_co_u32_e32 v6, vcc, s9, v16
	s_movk_i32 s9, 0x2000
	s_nop 0
	v_addc_co_u32_e32 v7, vcc, 0, v17, vcc
	v_add_co_u32_e32 v10, vcc, s9, v16
	s_movk_i32 s9, 0x3000
	s_nop 0
	v_addc_co_u32_e32 v11, vcc, 0, v17, vcc
	v_add_co_u32_e32 v14, vcc, s9, v16
	s_movk_i32 s9, 0x4000
	s_nop 0
	v_addc_co_u32_e32 v15, vcc, 0, v17, vcc
	v_add_co_u32_e32 v18, vcc, s9, v16
	s_movk_i32 s9, 0x5000
	s_nop 0
	v_addc_co_u32_e32 v19, vcc, 0, v17, vcc
	global_load_dword v0, v[16:17], off
	global_load_dword v2, v[16:17], off offset:2048
	global_load_dword v4, v[10:11], off offset:-4096
	s_nop 0
	global_load_dword v6, v[6:7], off offset:2048
	s_nop 0
	global_load_dword v8, v[10:11], off
	s_nop 0
	global_load_dword v10, v[10:11], off offset:2048
	s_nop 0
	global_load_dword v12, v[18:19], off offset:-4096
	s_nop 0
	global_load_dword v14, v[14:15], off offset:2048
	s_nop 0
	global_load_dword v1, v[18:19], off
	global_load_dword v3, v[18:19], off offset:2048
	v_add_co_u32_e32 v18, vcc, s9, v16
	s_movk_i32 s9, 0x6000
	s_nop 0
	v_addc_co_u32_e32 v19, vcc, 0, v17, vcc
	v_add_co_u32_e32 v20, vcc, s9, v16
	s_movk_i32 s9, 0x7000
	s_nop 0
	v_addc_co_u32_e32 v21, vcc, 0, v17, vcc
	v_add_co_u32_e32 v16, vcc, s9, v16
	global_load_dword v5, v[20:21], off offset:-4096
	global_load_dword v7, v[18:19], off offset:2048
	global_load_dword v9, v[20:21], off
	global_load_dword v11, v[20:21], off offset:2048
	v_addc_co_u32_e32 v17, vcc, 0, v17, vcc
	global_load_dword v13, v[16:17], off
	global_load_dword v15, v[16:17], off offset:2048
	v_lshl_add_u64 v[16:17], v[160:161], 0, v[90:91]
	v_lshlrev_b32_e32 v90, 1, v156
	global_load_dword v20, v[16:17], off
	v_lshl_add_u64 v[16:17], s[0:1], 0, v[90:91]
	v_lshl_add_u64 v[18:19], v[16:17], 0, v[162:163]
	global_load_ushort v21, v[18:19], off offset:1024
	v_lshl_add_u64 v[18:19], v[16:17], 0, v[164:165]
	global_load_ushort v36, v[18:19], off offset:1024
	v_lshl_add_u64 v[18:19], v[16:17], 0, v[166:167]
	global_load_ushort v22, v[18:19], off offset:1024
	v_lshl_add_u64 v[18:19], v[16:17], 0, v[168:169]
	global_load_ushort v37, v[18:19], off offset:1024
	v_lshl_add_u64 v[18:19], v[16:17], 0, v[170:171]
	global_load_ushort v34, v[18:19], off offset:1024
	v_lshl_add_u64 v[18:19], v[16:17], 0, v[172:173]
	global_load_ushort v23, v[18:19], off offset:1024
	v_lshl_add_u64 v[18:19], v[16:17], 0, v[174:175]
	global_load_ushort v35, v[18:19], off offset:1024
	v_lshl_add_u64 v[18:19], v[16:17], 0, v[176:177]
	global_load_ushort v18, v[18:19], off offset:1024
	s_waitcnt vmcnt(25)
	ds_write_b128 v157, v[240:243]
	v_perm_b32 v208, v209, v208, s3
	v_perm_b32 v209, v211, v210, s3
	v_perm_b32 v210, v213, v212, s3
	v_perm_b32 v211, v215, v214, s3
	v_perm_b32 v212, v217, v216, s3
	v_perm_b32 v213, v219, v218, s3
	v_perm_b32 v214, v221, v220, s3
	v_perm_b32 v215, v223, v222, s3
	v_perm_b32 v216, v225, v224, s3
	v_perm_b32 v217, v227, v226, s3
	v_perm_b32 v218, v229, v228, s3
	v_perm_b32 v219, v231, v230, s3
	v_perm_b32 v220, v233, v232, s3
	v_perm_b32 v221, v235, v234, s3
	v_perm_b32 v222, v237, v236, s3
	v_perm_b32 v223, v239, v238, s3
	ds_write_b128 v192, v[208:211]
	ds_write_b128 v192, v[212:215] offset:16
	ds_write_b128 v192, v[216:219] offset:32
	ds_write_b128 v193, v[220:223]
	s_mov_b32 s0, 8
	s_waitcnt lgkmcnt(0)
	s_barrier
	s_waitcnt vmcnt(8)
	v_mov_b32_e32 v90, v20
	s_waitcnt vmcnt(5)
	v_perm_b32 v33, v22, v21, s3
	s_waitcnt vmcnt(0)
	v_perm_b32 v28, v23, v18, s3

.LBB0_761:
	s_ashr_i32 s21, s43, 2
	s_lshl_b32 s24, s21, 6
	s_ashr_i32 s25, s24, 31
	s_lshl_b64 s[22:23], s[24:25], 7
	v_lshl_add_u64 v[0:1], v[56:57], 0, s[22:23]
	global_load_dwordx4 v[240:243], v[0:1], off
	s_and_b32 s11, s43, 3
	s_mul_i32 s0, s21, 0x60000
	s_mul_hi_i32 s10, s24, 0x1800
	s_add_u32 s0, s90, s0
	s_addc_u32 s10, s91, s10
	s_lshl_b32 s20, s11, 8
	s_lshl_b32 s22, s11, 9
	s_add_u32 s22, s0, s22
	s_addc_u32 s23, s10, 0
	v_mov_b32_e32 v157, v59
	v_mov_b32_e32 v17, v59
	v_lshl_add_u64 v[0:1], s[22:23], 0, v[156:157]
	v_lshl_add_u64 v[2:3], v[0:1], 0, v[60:61]
	global_load_ushort v208, v[2:3], off offset:2048
	v_lshl_add_u64 v[2:3], v[0:1], 0, v[62:63]
	global_load_ushort v209, v[2:3], off offset:2048
	v_lshl_add_u64 v[2:3], v[0:1], 0, v[64:65]
	global_load_ushort v210, v[2:3], off offset:2048
	v_lshl_add_u64 v[2:3], v[0:1], 0, v[66:67]
	global_load_ushort v211, v[2:3], off offset:2048
	v_lshl_add_u64 v[2:3], v[0:1], 0, v[68:69]
	global_load_ushort v212, v[2:3], off offset:2048
	v_lshl_add_u64 v[2:3], v[0:1], 0, v[70:71]
	global_load_ushort v213, v[2:3], off offset:2048
	v_lshl_add_u64 v[2:3], v[0:1], 0, v[72:73]
	global_load_ushort v214, v[2:3], off offset:2048
	v_lshl_add_u64 v[2:3], v[0:1], 0, v[74:75]
	global_load_ushort v215, v[2:3], off offset:2048
	s_lshl_b32 s22, s11, 7
	s_movk_i32 s11, 0x2000
	s_add_u32 s44, s0, s20
	s_addc_u32 s45, s10, 0
	v_lshl_add_u64 v[2:3], v[0:1], 0, v[76:77]
	global_load_ushort v216, v[2:3], off offset:2048
	v_lshl_add_u64 v[2:3], v[0:1], 0, v[78:79]
	global_load_ushort v217, v[2:3], off offset:2048
	v_lshl_add_u64 v[2:3], v[0:1], 0, v[80:81]
	global_load_ushort v218, v[2:3], off offset:2048
	v_lshl_add_u64 v[2:3], v[0:1], 0, v[82:83]
	global_load_ushort v219, v[2:3], off offset:2048
	v_lshl_add_u64 v[2:3], v[0:1], 0, v[84:85]
	global_load_ushort v220, v[2:3], off offset:2048
	v_lshl_add_u64 v[2:3], v[0:1], 0, v[86:87]
	global_load_ushort v221, v[2:3], off offset:2048
	v_lshl_add_u64 v[2:3], v[0:1], 0, v[88:89]
	global_load_ushort v222, v[2:3], off offset:2048
	v_lshl_add_u64 v[2:3], v[0:1], 0, v[90:91]
	global_load_ushort v223, v[2:3], off offset:2048
	v_lshl_add_u64 v[2:3], v[0:1], 0, v[92:93]
	global_load_ushort v224, v[2:3], off offset:2048
	v_lshl_add_u64 v[2:3], v[0:1], 0, v[94:95]
	global_load_ushort v225, v[2:3], off offset:2048
	v_lshl_add_u64 v[2:3], v[0:1], 0, v[96:97]
	global_load_ushort v226, v[2:3], off offset:2048
	v_lshl_add_u64 v[2:3], v[0:1], 0, v[98:99]
	global_load_ushort v227, v[2:3], off offset:2048
	v_lshl_add_u64 v[2:3], v[0:1], 0, v[100:101]
	global_load_ushort v228, v[2:3], off offset:2048
	v_lshl_add_u64 v[2:3], v[0:1], 0, v[102:103]
	global_load_ushort v229, v[2:3], off offset:2048
	v_lshl_add_u64 v[2:3], v[0:1], 0, v[104:105]
	global_load_ushort v230, v[2:3], off offset:2048
	v_lshl_add_u64 v[2:3], v[0:1], 0, v[106:107]
	global_load_ushort v231, v[2:3], off offset:2048
	v_lshl_add_u64 v[2:3], v[0:1], 0, v[108:109]
	global_load_ushort v232, v[2:3], off offset:2048
	v_lshl_add_u64 v[2:3], v[0:1], 0, v[110:111]
	global_load_ushort v233, v[2:3], off offset:2048
	v_lshl_add_u64 v[2:3], v[0:1], 0, v[112:113]
	global_load_ushort v234, v[2:3], off offset:2048
	v_lshl_add_u64 v[2:3], v[0:1], 0, v[114:115]
	global_load_ushort v235, v[2:3], off offset:2048
	v_lshl_add_u64 v[2:3], v[0:1], 0, v[116:117]
	global_load_ushort v236, v[2:3], off offset:2048
	v_lshl_add_u64 v[2:3], v[0:1], 0, v[118:119]
	global_load_ushort v237, v[2:3], off offset:2048
	v_lshl_add_u64 v[2:3], v[0:1], 0, v[120:121]
	v_lshl_add_u64 v[0:1], v[0:1], 0, v[122:123]
	global_load_ushort v238, v[2:3], off offset:2048
	global_load_ushort v239, v[0:1], off offset:2048
	v_or_b32_e32 v0, s22, v124
	v_lshlrev_b32_e32 v16, 2, v0
	v_lshl_add_u64 v[18:19], v[126:127], 0, v[16:17]
	v_add_co_u32_e32 v6, vcc, s31, v18
	global_load_dword v0, v[18:19], off
	global_load_dword v2, v[18:19], off offset:2048
	v_addc_co_u32_e32 v7, vcc, 0, v19, vcc
	v_add_co_u32_e32 v10, vcc, s11, v18
	s_movk_i32 s11, 0x3000
	s_nop 0
	v_addc_co_u32_e32 v11, vcc, 0, v19, vcc
	v_add_co_u32_e32 v14, vcc, s11, v18
	s_movk_i32 s11, 0x4000
	s_nop 0
	v_addc_co_u32_e32 v15, vcc, 0, v19, vcc
	v_add_co_u32_e32 v20, vcc, s11, v18
	s_movk_i32 s11, 0x5000
	s_nop 0
	v_addc_co_u32_e32 v21, vcc, 0, v19, vcc
	global_load_dword v4, v[10:11], off offset:-4096
	s_nop 0
	global_load_dword v6, v[6:7], off offset:2048
	s_nop 0
	global_load_dword v8, v[10:11], off
	s_nop 0
	global_load_dword v10, v[10:11], off offset:2048
	s_nop 0
	global_load_dword v12, v[20:21], off offset:-4096
	s_nop 0
	global_load_dword v14, v[14:15], off offset:2048
	s_nop 0
	global_load_dword v1, v[20:21], off
	global_load_dword v3, v[20:21], off offset:2048
	v_add_co_u32_e32 v20, vcc, s11, v18
	s_movk_i32 s11, 0x6000
	s_nop 0
	v_addc_co_u32_e32 v21, vcc, 0, v19, vcc
	v_add_co_u32_e32 v22, vcc, s11, v18
	s_movk_i32 s11, 0x7000
	s_nop 0
	v_addc_co_u32_e32 v23, vcc, 0, v19, vcc
	v_add_co_u32_e32 v18, vcc, s11, v18
	global_load_dword v5, v[22:23], off offset:-4096
	global_load_dword v7, v[20:21], off offset:2048
	global_load_dword v9, v[22:23], off
	global_load_dword v11, v[22:23], off offset:2048
	v_addc_co_u32_e32 v19, vcc, 0, v19, vcc
	global_load_dword v13, v[18:19], off
	global_load_dword v15, v[18:19], off offset:2048
	v_lshlrev_b32_e32 v18, 1, v124
	v_mov_b32_e32 v19, v59
	v_lshl_add_u64 v[18:19], s[44:45], 0, v[18:19]
	v_lshl_add_u64 v[16:17], v[128:129], 0, v[16:17]
	v_lshl_add_u64 v[20:21], v[18:19], 0, v[130:131]
	global_load_dword v16, v[16:17], off
	s_waitcnt vmcnt(17)
	ds_write_b128 v125, v[240:243]
	v_perm_b32 v208, v209, v208, s30
	v_perm_b32 v209, v211, v210, s30
	v_perm_b32 v210, v213, v212, s30
	v_perm_b32 v211, v215, v214, s30
	v_perm_b32 v212, v217, v216, s30
	v_perm_b32 v213, v219, v218, s30
	v_perm_b32 v214, v221, v220, s30
	v_perm_b32 v215, v223, v222, s30
	v_perm_b32 v216, v225, v224, s30
	v_perm_b32 v217, v227, v226, s30
	v_perm_b32 v218, v229, v228, s30
	v_perm_b32 v219, v231, v230, s30
	v_perm_b32 v220, v233, v232, s30
	v_perm_b32 v221, v235, v234, s30
	v_perm_b32 v222, v237, v236, s30
	v_perm_b32 v223, v239, v238, s30
	ds_write_b128 v160, v[208:211]
	ds_write_b128 v160, v[212:215] offset:16
	ds_write_b128 v160, v[216:219] offset:32
	ds_write_b128 v161, v[220:223]
	s_nop 0
	global_load_ushort v36, v[20:21], off
	global_load_ushort v37, v[20:21], off offset:1024
	v_lshl_add_u64 v[20:21], v[18:19], 0, v[132:133]
	global_load_ushort v34, v[20:21], off
	global_load_ushort v35, v[20:21], off offset:1024
	v_lshl_add_u64 v[20:21], v[18:19], 0, v[134:135]
	global_load_ushort v32, v[20:21], off
	global_load_ushort v33, v[20:21], off offset:1024
	v_lshl_add_u64 v[20:21], v[18:19], 0, v[136:137]
	global_load_ushort v30, v[20:21], off
	global_load_ushort v31, v[20:21], off offset:1024
	v_lshl_add_u64 v[20:21], v[18:19], 0, v[138:139]
	global_load_ushort v28, v[20:21], off
	global_load_ushort v29, v[20:21], off offset:1024
	v_lshl_add_u64 v[20:21], v[18:19], 0, v[140:141]
	global_load_ushort v26, v[20:21], off
	global_load_ushort v27, v[20:21], off offset:1024
	v_lshl_add_u64 v[20:21], v[18:19], 0, v[142:143]
	global_load_ushort v24, v[20:21], off
	global_load_ushort v25, v[20:21], off offset:1024
	v_lshl_add_u64 v[20:21], v[18:19], 0, v[144:145]
	global_load_ushort v22, v[20:21], off
	global_load_ushort v23, v[20:21], off offset:1024
	v_mov_b32_e32 v20, v59
	s_and_saveexec_b64 s[10:11], s[6:7]
	s_cbranch_execz .LBB0_763
	v_add_u32_e32 v20, s21, v162
	v_ashrrev_i32_e32 v21, 31, v20
	v_lshlrev_b64 v[20:21], 11, v[20:21]
	v_lshl_add_u64 v[20:21], s[74:75], 0, v[20:21]
	s_lshl_b32 s0, s22, 2
	v_lshl_add_u64 v[20:21], v[20:21], 0, s[0:1]
	v_lshlrev_b32_e32 v38, 2, v124
	v_mov_b32_e32 v39, v59
	v_lshl_add_u64 v[20:21], v[20:21], 0, v[38:39]
	global_load_dword v20, v[20:21], off
